# grid barrier: the XCD leader bumps its XCD's generation word before its own acquire invalidate (was after)
# speedup vs baseline: 1.0113x; 1.0061x over previous
.LBB0_266:
	s_or_b64 exec, exec, s[10:11]
	buffer_inv sc1
	s_waitcnt vmcnt(0)

.LBB0_321:
	s_or_b64 exec, exec, s[8:9]
	s_mov_b64 s[8:9], exec
	v_mbcnt_lo_u32_b32 v0, s8, 0
	v_mbcnt_hi_u32_b32 v0, s9, v0
	v_cmp_eq_u32_e32 vcc, 0, v0
	s_waitcnt vmcnt(0)
	s_and_saveexec_b64 s[10:11], vcc
	s_cbranch_execz .LBB0_323
	s_bcnt1_i32_b64 s8, s[8:9]
	v_mov_b32_e32 v0, s8
	v_readlane_b32 s8, v253, 5
	v_readlane_b32 s9, v253, 6
	s_nop 4
	global_atomic_add v113, v0, s[8:9]

.LBB0_383:
	s_or_b64 exec, exec, s[6:7]
	s_mov_b64 s[6:7], exec
	v_mbcnt_lo_u32_b32 v0, s6, 0
	v_mbcnt_hi_u32_b32 v0, s7, v0
	v_cmp_eq_u32_e32 vcc, 0, v0
	s_waitcnt vmcnt(0)
	s_and_saveexec_b64 s[8:9], vcc
	s_cbranch_execz .LBB0_385
	s_bcnt1_i32_b64 s6, s[6:7]
	v_mov_b32_e32 v0, s6
	v_readlane_b32 s6, v253, 5
	v_readlane_b32 s7, v253, 6
	s_nop 4
	global_atomic_add v113, v0, s[6:7]
.LBB0_385:
	s_or_b64 exec, exec, s[8:9]
	buffer_inv sc1
	s_waitcnt vmcnt(0)

.LBB0_1616:
	s_or_b64 exec, exec, s[8:9]
	s_mov_b64 s[8:9], exec
	v_mbcnt_lo_u32_b32 v0, s8, 0
	v_mbcnt_hi_u32_b32 v0, s9, v0
	v_cmp_eq_u32_e32 vcc, 0, v0
	s_waitcnt vmcnt(0)
	s_and_saveexec_b64 s[10:11], vcc
	s_cbranch_execz .LBB0_266
	s_bcnt1_i32_b64 s8, s[8:9]
	v_mov_b32_e32 v0, s8
	v_readlane_b32 s8, v253, 5
	v_readlane_b32 s9, v253, 6
	s_nop 4
	global_atomic_add v113, v0, s[8:9]
	s_branch .LBB0_266

.LBB0_1673:
	s_or_b64 exec, exec, s[10:11]
	s_mov_b64 s[10:11], exec
	v_mbcnt_lo_u32_b32 v0, s10, 0
	v_mbcnt_hi_u32_b32 v0, s11, v0
	v_cmp_eq_u32_e32 vcc, 0, v0
	s_waitcnt vmcnt(0)
	s_and_saveexec_b64 s[12:13], vcc
	s_cbranch_execz .LBB0_1675
	s_bcnt1_i32_b64 s10, s[10:11]
	v_mov_b32_e32 v0, s10
	v_readlane_b32 s10, v253, 5
	v_readlane_b32 s11, v253, 6
	s_nop 4
	global_atomic_add v113, v0, s[10:11]
.LBB0_1675:
	s_or_b64 exec, exec, s[12:13]
	buffer_inv sc1
	s_waitcnt vmcnt(0)

.LBB0_1741:
	s_or_b64 exec, exec, s[12:13]
	s_mov_b64 s[12:13], exec
	v_mbcnt_lo_u32_b32 v0, s12, 0
	v_mbcnt_hi_u32_b32 v0, s13, v0
	v_cmp_eq_u32_e32 vcc, 0, v0
	s_waitcnt vmcnt(0)
	s_and_saveexec_b64 s[14:15], vcc
	s_cbranch_execz .LBB0_1743
	s_bcnt1_i32_b64 s12, s[12:13]
	v_mov_b32_e32 v0, s12
	v_readlane_b32 s12, v253, 5
	v_readlane_b32 s13, v253, 6
	s_nop 4
	global_atomic_add v113, v0, s[12:13]
.LBB0_1743:
	s_or_b64 exec, exec, s[14:15]
	buffer_inv sc1
	s_waitcnt vmcnt(0)
